# selected-branch tiles: running-max reference updated (and accumulators rescaled) only when a row's tile max exceeds it by more than 8 in log2 units; f32 sums/accumulators unchanged; plus sink scalar p
# speedup vs baseline: 1.0050x; 1.0050x over previous
.Lp1v_s0:
	s_cmp_lg_u64 s[44:45], 0
	s_cbranch_scc0 .Lp1v_z0
	s_waitcnt lgkmcnt(0)
	v_pk_fma_f32 v[170:171], v[170:171], s[36:37], v[90:91] op_sel_hi:[1,0,1]
	v_pk_fma_f32 v[172:173], v[172:173], s[36:37], v[92:93] op_sel_hi:[1,0,1]
	v_pk_fma_f32 v[174:175], v[174:175], s[36:37], v[94:95] op_sel_hi:[1,0,1]
	v_pk_fma_f32 v[176:177], v[176:177], s[36:37], v[96:97] op_sel_hi:[1,0,1]
	v_pk_fma_f32 v[178:179], v[178:179], s[36:37], v[98:99] op_sel_hi:[1,0,1]
	v_pk_fma_f32 v[180:181], v[180:181], s[36:37], v[100:101] op_sel_hi:[1,0,1]
	v_pk_fma_f32 v[182:183], v[182:183], s[36:37], v[154:155] op_sel_hi:[1,0,1]
	v_pk_fma_f32 v[184:185], v[184:185], s[36:37], v[156:157] op_sel_hi:[1,0,1]
	ds_read2_b32 v[90:91], v231 offset1:1
	ds_read2_b32 v[92:93], v231 offset0:2 offset1:3
	ds_read2_b32 v[94:95], v231 offset0:16 offset1:17
	ds_read2_b32 v[96:97], v231 offset0:18 offset1:19
	ds_read2_b32 v[98:99], v231 offset0:32 offset1:33
	ds_read2_b32 v[100:101], v231 offset0:34 offset1:35
	ds_read2_b32 v[154:155], v231 offset0:48 offset1:49
	ds_read2_b32 v[156:157], v231 offset0:50 offset1:51
	v_max3_f32 v186, v170, v171, v172
	v_max3_f32 v186, v186, v173, v174
	v_max3_f32 v186, v186, v175, v176
	v_max3_f32 v186, v186, v177, v178
	v_max3_f32 v186, v186, v179, v180
	v_max3_f32 v186, v186, v181, v182
	v_max3_f32 v186, v186, v183, v184
	v_max3_f32 v186, v186, v185, s29
	v_mov_b32_e32 v187, v186
	s_nop 1
	v_permlane16_swap_b32_e32 v186, v187
	v_max_f32_e32 v186, v186, v187
	v_mov_b32_e32 v187, v186
	s_nop 1
	v_permlane32_swap_b32_e32 v186, v187
	v_max_f32_e32 v186, v186, v187
	v_cndmask_b32_e64 v186, v148, v186, s[44:45]
	v_add_f32_e32 v187, 0xc1000000, v186
	v_cmp_gt_f32_e32 vcc, v187, v160
	s_cbranch_vccnz .Llz1_slow
	v_cndmask_b32_e64 v246, v209, v160, s[44:45]
	v_mov_b32_e32 v236, 1.0
	s_branch .Llz1_tail
.Llz1_slow:
	v_max_f32_e32 v187, v160, v186
	v_sub_f32_e32 v248, v160, v187
	v_exp_f32_e32 v236, v248
	v_cndmask_b32_e64 v246, v209, v187, s[44:45]
	v_mov_b32_e32 v160, v187
	v_pk_mul_f32 v[36:37], v[36:37], v[236:237] op_sel_hi:[1,0]
	v_pk_mul_f32 v[34:35], v[34:35], v[236:237] op_sel_hi:[1,0]
	v_pk_mul_f32 v[48:49], v[48:49], v[236:237] op_sel_hi:[1,0]
	v_pk_mul_f32 v[46:47], v[46:47], v[236:237] op_sel_hi:[1,0]
	v_pk_mul_f32 v[44:45], v[44:45], v[236:237] op_sel_hi:[1,0]
	v_pk_mul_f32 v[42:43], v[42:43], v[236:237] op_sel_hi:[1,0]
	v_pk_mul_f32 v[52:53], v[52:53], v[236:237] op_sel_hi:[1,0]
	v_pk_mul_f32 v[50:51], v[50:51], v[236:237] op_sel_hi:[1,0]
.Llz1_tail:
	v_pk_add_f32 v[170:171], v[170:171], v[246:247] op_sel_hi:[1,0] neg_lo:[0,1] neg_hi:[0,1]
	v_pk_add_f32 v[172:173], v[172:173], v[246:247] op_sel_hi:[1,0] neg_lo:[0,1] neg_hi:[0,1]
	v_pk_add_f32 v[174:175], v[174:175], v[246:247] op_sel_hi:[1,0] neg_lo:[0,1] neg_hi:[0,1]
	v_pk_add_f32 v[176:177], v[176:177], v[246:247] op_sel_hi:[1,0] neg_lo:[0,1] neg_hi:[0,1]
	v_pk_add_f32 v[178:179], v[178:179], v[246:247] op_sel_hi:[1,0] neg_lo:[0,1] neg_hi:[0,1]
	v_pk_add_f32 v[180:181], v[180:181], v[246:247] op_sel_hi:[1,0] neg_lo:[0,1] neg_hi:[0,1]
	v_pk_add_f32 v[182:183], v[182:183], v[246:247] op_sel_hi:[1,0] neg_lo:[0,1] neg_hi:[0,1]
	v_pk_add_f32 v[184:185], v[184:185], v[246:247] op_sel_hi:[1,0] neg_lo:[0,1] neg_hi:[0,1]
	v_exp_f32_e32 v170, v170
	v_exp_f32_e32 v171, v171
	v_exp_f32_e32 v172, v172
	v_exp_f32_e32 v173, v173
	v_exp_f32_e32 v174, v174
	v_exp_f32_e32 v175, v175
	v_exp_f32_e32 v176, v176
	v_exp_f32_e32 v177, v177
	v_exp_f32_e32 v178, v178
	v_exp_f32_e32 v179, v179
	v_exp_f32_e32 v180, v180
	v_exp_f32_e32 v181, v181
	v_exp_f32_e32 v182, v182
	v_exp_f32_e32 v183, v183
	v_exp_f32_e32 v184, v184
	v_exp_f32_e32 v185, v185
	s_nop 0
	v_pk_add_f32 v[238:239], v[170:171], v[172:173]
	v_pk_add_f32 v[240:241], v[174:175], v[176:177]
	v_pk_add_f32 v[242:243], v[178:179], v[180:181]
	v_pk_add_f32 v[244:245], v[182:183], v[184:185]
	v_pk_add_f32 v[238:239], v[238:239], v[240:241]
	v_pk_add_f32 v[242:243], v[242:243], v[244:245]
	s_nop 0
	v_pk_add_f32 v[238:239], v[238:239], v[242:243]
	s_nop 0
	v_add_f32_e32 v238, v238, v239
	v_fma_f32 v144, v144, v236, v238
	v_cvt_pk_bf16_f32 v58, v170, v171
	v_cvt_pk_bf16_f32 v59, v172, v173
	v_cvt_pk_bf16_f32 v60, v174, v175
	v_cvt_pk_bf16_f32 v61, v176, v177
	v_cvt_pk_bf16_f32 v54, v178, v179
	v_cvt_pk_bf16_f32 v55, v180, v181
	v_cvt_pk_bf16_f32 v56, v182, v183
	v_cvt_pk_bf16_f32 v57, v184, v185
	s_branch .Lp1v_s1

.Lp1v_s1:
	s_cmp_lg_u64 s[42:43], 0
	s_cbranch_scc0 .LBB0_445
	s_waitcnt lgkmcnt(0)
	v_pk_fma_f32 v[64:65], v[64:65], s[36:37], v[90:91] op_sel_hi:[1,0,1]
	v_pk_fma_f32 v[66:67], v[66:67], s[36:37], v[92:93] op_sel_hi:[1,0,1]
	v_pk_fma_f32 v[68:69], v[68:69], s[36:37], v[94:95] op_sel_hi:[1,0,1]
	v_pk_fma_f32 v[70:71], v[70:71], s[36:37], v[96:97] op_sel_hi:[1,0,1]
	v_pk_fma_f32 v[72:73], v[72:73], s[36:37], v[98:99] op_sel_hi:[1,0,1]
	v_pk_fma_f32 v[74:75], v[74:75], s[36:37], v[100:101] op_sel_hi:[1,0,1]
	v_pk_fma_f32 v[80:81], v[80:81], s[36:37], v[154:155] op_sel_hi:[1,0,1]
	v_pk_fma_f32 v[82:83], v[82:83], s[36:37], v[156:157] op_sel_hi:[1,0,1]
	v_max3_f32 v76, v64, v65, v66
	v_max3_f32 v76, v76, v67, v68
	v_max3_f32 v76, v76, v69, v70
	v_max3_f32 v76, v76, v71, v72
	v_max3_f32 v76, v76, v73, v74
	v_max3_f32 v76, v76, v75, v80
	v_max3_f32 v76, v76, v81, v82
	v_max3_f32 v76, v76, v83, s29
	v_mov_b32_e32 v77, v76
	s_nop 1
	v_permlane16_swap_b32_e32 v76, v77
	v_max_f32_e32 v76, v76, v77
	v_mov_b32_e32 v77, v76
	s_nop 1
	v_permlane32_swap_b32_e32 v76, v77
	v_max_f32_e32 v76, v76, v77
	v_cndmask_b32_e64 v76, v148, v76, s[42:43]
	v_add_f32_e32 v77, 0xc1000000, v76
	v_cmp_gt_f32_e32 vcc, v77, v161
	s_cbranch_vccnz .Llz2_slow
	v_cndmask_b32_e64 v78, v209, v161, s[42:43]
	v_mov_b32_e32 v0, 1.0
	s_branch .Llz2_tail
.Llz2_slow:
	v_max_f32_e32 v77, v161, v76
	v_sub_f32_e32 v0, v161, v77
	v_exp_f32_e32 v0, v0
	v_cndmask_b32_e64 v78, v209, v77, s[42:43]
	v_mov_b32_e32 v161, v77
	v_pk_mul_f32 v[32:33], v[32:33], v[0:1] op_sel_hi:[1,0]
	v_pk_mul_f32 v[30:31], v[30:31], v[0:1] op_sel_hi:[1,0]
	v_pk_mul_f32 v[28:29], v[28:29], v[0:1] op_sel_hi:[1,0]
	v_pk_mul_f32 v[26:27], v[26:27], v[0:1] op_sel_hi:[1,0]
	v_pk_mul_f32 v[24:25], v[24:25], v[0:1] op_sel_hi:[1,0]
	v_pk_mul_f32 v[22:23], v[22:23], v[0:1] op_sel_hi:[1,0]
	v_pk_mul_f32 v[20:21], v[20:21], v[0:1] op_sel_hi:[1,0]
	v_pk_mul_f32 v[18:19], v[18:19], v[0:1] op_sel_hi:[1,0]
.Llz2_tail:
	v_pk_add_f32 v[64:65], v[64:65], v[78:79] op_sel_hi:[1,0] neg_lo:[0,1] neg_hi:[0,1]
	v_pk_add_f32 v[66:67], v[66:67], v[78:79] op_sel_hi:[1,0] neg_lo:[0,1] neg_hi:[0,1]
	v_pk_add_f32 v[68:69], v[68:69], v[78:79] op_sel_hi:[1,0] neg_lo:[0,1] neg_hi:[0,1]
	v_pk_add_f32 v[70:71], v[70:71], v[78:79] op_sel_hi:[1,0] neg_lo:[0,1] neg_hi:[0,1]
	v_pk_add_f32 v[72:73], v[72:73], v[78:79] op_sel_hi:[1,0] neg_lo:[0,1] neg_hi:[0,1]
	v_pk_add_f32 v[74:75], v[74:75], v[78:79] op_sel_hi:[1,0] neg_lo:[0,1] neg_hi:[0,1]
	v_pk_add_f32 v[80:81], v[80:81], v[78:79] op_sel_hi:[1,0] neg_lo:[0,1] neg_hi:[0,1]
	v_pk_add_f32 v[82:83], v[82:83], v[78:79] op_sel_hi:[1,0] neg_lo:[0,1] neg_hi:[0,1]
	v_exp_f32_e32 v64, v64
	v_exp_f32_e32 v65, v65
	v_exp_f32_e32 v66, v66
	v_exp_f32_e32 v67, v67
	v_exp_f32_e32 v68, v68
	v_exp_f32_e32 v69, v69
	v_exp_f32_e32 v70, v70
	v_exp_f32_e32 v71, v71
	v_exp_f32_e32 v72, v72
	v_exp_f32_e32 v73, v73
	v_exp_f32_e32 v74, v74
	v_exp_f32_e32 v75, v75
	v_exp_f32_e32 v80, v80
	v_exp_f32_e32 v81, v81
	v_exp_f32_e32 v82, v82
	v_exp_f32_e32 v83, v83
	s_nop 0
	v_pk_add_f32 v[84:85], v[64:65], v[66:67]
	v_pk_add_f32 v[86:87], v[68:69], v[70:71]
	v_pk_add_f32 v[76:77], v[72:73], v[74:75]
	v_pk_add_f32 v[78:79], v[80:81], v[82:83]
	v_pk_add_f32 v[84:85], v[84:85], v[86:87]
	v_pk_add_f32 v[76:77], v[76:77], v[78:79]
	s_nop 0
	v_pk_add_f32 v[84:85], v[84:85], v[76:77]
	s_nop 0
	v_add_f32_e32 v84, v84, v85
	v_fma_f32 v145, v145, v0, v84
	v_cvt_pk_bf16_f32 v67, v66, v67
	v_cvt_pk_bf16_f32 v66, v64, v65
	v_cvt_pk_bf16_f32 v68, v68, v69
	v_cvt_pk_bf16_f32 v69, v70, v71
	v_cvt_pk_bf16_f32 v62, v72, v73
	v_cvt_pk_bf16_f32 v63, v74, v75
	v_cvt_pk_bf16_f32 v64, v80, v81
	v_cvt_pk_bf16_f32 v65, v82, v83
	s_branch .LBB0_446

.Lp2v_s0:
	s_cmp_lg_u64 s[44:45], 0
	s_cbranch_scc0 .Lp2v_z0
	v_max3_f32 v186, v170, v171, v172
	v_max3_f32 v186, v186, v173, v174
	v_max3_f32 v186, v186, v175, v176
	v_max3_f32 v186, v186, v177, v178
	v_max3_f32 v186, v186, v179, v180
	v_max3_f32 v186, v186, v181, v182
	v_max3_f32 v186, v186, v183, v184
	v_max_f32_e32 v186, v186, v185
	v_mov_b32_e32 v187, v186
	s_nop 1
	v_permlane16_swap_b32_e32 v186, v187
	v_max_f32_e32 v186, v186, v187
	v_mov_b32_e32 v187, v186
	s_nop 1
	v_permlane32_swap_b32_e32 v186, v187
	v_max_f32_e32 v186, v186, v187
	v_fma_f32 v186, v186, s36, v188
	v_max_f32_e32 v186, s29, v186
	v_cndmask_b32_e64 v186, v148, v186, s[44:45]
	v_add_f32_e32 v187, 0xc1000000, v186
	v_cmp_gt_f32_e32 vcc, v187, v160
	s_cbranch_vccnz .Llz3_slow
	v_cndmask_b32_e64 v186, v209, v160, s[44:45]
	v_sub_f32_e32 v246, v188, v186
	v_mov_b32_e32 v236, 1.0
	s_branch .Llz3_tail
.Llz3_slow:
	v_max_f32_e32 v187, v160, v186
	v_sub_f32_e32 v248, v160, v187
	v_exp_f32_e32 v236, v248
	v_cndmask_b32_e64 v186, v209, v187, s[44:45]
	v_mov_b32_e32 v160, v187
	v_sub_f32_e32 v246, v188, v186
	v_pk_mul_f32 v[36:37], v[36:37], v[236:237] op_sel_hi:[1,0]
	v_pk_mul_f32 v[34:35], v[34:35], v[236:237] op_sel_hi:[1,0]
	v_pk_mul_f32 v[48:49], v[48:49], v[236:237] op_sel_hi:[1,0]
	v_pk_mul_f32 v[46:47], v[46:47], v[236:237] op_sel_hi:[1,0]
	v_pk_mul_f32 v[44:45], v[44:45], v[236:237] op_sel_hi:[1,0]
	v_pk_mul_f32 v[42:43], v[42:43], v[236:237] op_sel_hi:[1,0]
	v_pk_mul_f32 v[52:53], v[52:53], v[236:237] op_sel_hi:[1,0]
	v_pk_mul_f32 v[50:51], v[50:51], v[236:237] op_sel_hi:[1,0]
.Llz3_tail:
	v_pk_fma_f32 v[170:171], v[170:171], s[36:37], v[246:247] op_sel_hi:[1,0,0]
	v_pk_fma_f32 v[172:173], v[172:173], s[36:37], v[246:247] op_sel_hi:[1,0,0]
	v_pk_fma_f32 v[174:175], v[174:175], s[36:37], v[246:247] op_sel_hi:[1,0,0]
	v_pk_fma_f32 v[176:177], v[176:177], s[36:37], v[246:247] op_sel_hi:[1,0,0]
	v_pk_fma_f32 v[178:179], v[178:179], s[36:37], v[246:247] op_sel_hi:[1,0,0]
	v_pk_fma_f32 v[180:181], v[180:181], s[36:37], v[246:247] op_sel_hi:[1,0,0]
	v_pk_fma_f32 v[182:183], v[182:183], s[36:37], v[246:247] op_sel_hi:[1,0,0]
	v_pk_fma_f32 v[184:185], v[184:185], s[36:37], v[246:247] op_sel_hi:[1,0,0]
	v_exp_f32_e32 v170, v170
	v_exp_f32_e32 v171, v171
	v_exp_f32_e32 v172, v172
	v_exp_f32_e32 v173, v173
	v_exp_f32_e32 v174, v174
	v_exp_f32_e32 v175, v175
	v_exp_f32_e32 v176, v176
	v_exp_f32_e32 v177, v177
	v_exp_f32_e32 v178, v178
	v_exp_f32_e32 v179, v179
	v_exp_f32_e32 v180, v180
	v_exp_f32_e32 v181, v181
	v_exp_f32_e32 v182, v182
	v_exp_f32_e32 v183, v183
	v_exp_f32_e32 v184, v184
	v_exp_f32_e32 v185, v185
	s_nop 0
	v_pk_add_f32 v[238:239], v[170:171], v[172:173]
	v_pk_add_f32 v[240:241], v[174:175], v[176:177]
	v_pk_add_f32 v[242:243], v[178:179], v[180:181]
	v_pk_add_f32 v[244:245], v[182:183], v[184:185]
	v_pk_add_f32 v[238:239], v[238:239], v[240:241]
	v_pk_add_f32 v[242:243], v[242:243], v[244:245]
	s_nop 0
	v_pk_add_f32 v[238:239], v[238:239], v[242:243]
	s_nop 0
	v_add_f32_e32 v238, v238, v239
	v_fma_f32 v144, v144, v236, v238
	v_cvt_pk_bf16_f32 v58, v170, v171
	v_cvt_pk_bf16_f32 v59, v172, v173
	v_cvt_pk_bf16_f32 v60, v174, v175
	v_cvt_pk_bf16_f32 v61, v176, v177
	v_cvt_pk_bf16_f32 v54, v178, v179
	v_cvt_pk_bf16_f32 v55, v180, v181
	v_cvt_pk_bf16_f32 v56, v182, v183
	v_cvt_pk_bf16_f32 v57, v184, v185
	s_branch .Lp2v_s1

.Lp2v_s1:
	s_cmp_lg_u64 s[42:43], 0
	s_cbranch_scc0 .LBB0_445
	v_max3_f32 v76, v64, v65, v66
	v_max3_f32 v76, v76, v67, v68
	v_max3_f32 v76, v76, v69, v70
	v_max3_f32 v76, v76, v71, v72
	v_max3_f32 v76, v76, v73, v74
	v_max3_f32 v76, v76, v75, v80
	v_max3_f32 v76, v76, v81, v82
	v_max_f32_e32 v76, v76, v83
	v_mov_b32_e32 v77, v76
	s_nop 1
	v_permlane16_swap_b32_e32 v76, v77
	v_max_f32_e32 v76, v76, v77
	v_mov_b32_e32 v77, v76
	s_nop 1
	v_permlane32_swap_b32_e32 v76, v77
	v_max_f32_e32 v76, v76, v77
	v_fma_f32 v76, v76, s36, v188
	v_max_f32_e32 v76, s29, v76
	v_cndmask_b32_e64 v76, v148, v76, s[42:43]
	v_add_f32_e32 v77, 0xc1000000, v76
	v_cmp_gt_f32_e32 vcc, v77, v161
	s_cbranch_vccnz .Llz4_slow
	v_cndmask_b32_e64 v76, v209, v161, s[42:43]
	v_sub_f32_e32 v78, v188, v76
	v_mov_b32_e32 v0, 1.0
	s_branch .Llz4_tail
.Llz4_slow:
	v_max_f32_e32 v77, v161, v76
	v_sub_f32_e32 v0, v161, v77
	v_exp_f32_e32 v0, v0
	v_cndmask_b32_e64 v76, v209, v77, s[42:43]
	v_mov_b32_e32 v161, v77
	v_sub_f32_e32 v78, v188, v76
	v_pk_mul_f32 v[32:33], v[32:33], v[0:1] op_sel_hi:[1,0]
	v_pk_mul_f32 v[30:31], v[30:31], v[0:1] op_sel_hi:[1,0]
	v_pk_mul_f32 v[28:29], v[28:29], v[0:1] op_sel_hi:[1,0]
	v_pk_mul_f32 v[26:27], v[26:27], v[0:1] op_sel_hi:[1,0]
	v_pk_mul_f32 v[24:25], v[24:25], v[0:1] op_sel_hi:[1,0]
	v_pk_mul_f32 v[22:23], v[22:23], v[0:1] op_sel_hi:[1,0]
	v_pk_mul_f32 v[20:21], v[20:21], v[0:1] op_sel_hi:[1,0]
	v_pk_mul_f32 v[18:19], v[18:19], v[0:1] op_sel_hi:[1,0]
.Llz4_tail:
	v_pk_fma_f32 v[64:65], v[64:65], s[36:37], v[78:79] op_sel_hi:[1,0,0]
	v_pk_fma_f32 v[66:67], v[66:67], s[36:37], v[78:79] op_sel_hi:[1,0,0]
	v_pk_fma_f32 v[68:69], v[68:69], s[36:37], v[78:79] op_sel_hi:[1,0,0]
	v_pk_fma_f32 v[70:71], v[70:71], s[36:37], v[78:79] op_sel_hi:[1,0,0]
	v_pk_fma_f32 v[72:73], v[72:73], s[36:37], v[78:79] op_sel_hi:[1,0,0]
	v_pk_fma_f32 v[74:75], v[74:75], s[36:37], v[78:79] op_sel_hi:[1,0,0]
	v_pk_fma_f32 v[80:81], v[80:81], s[36:37], v[78:79] op_sel_hi:[1,0,0]
	v_pk_fma_f32 v[82:83], v[82:83], s[36:37], v[78:79] op_sel_hi:[1,0,0]
	v_exp_f32_e32 v64, v64
	v_exp_f32_e32 v65, v65
	v_exp_f32_e32 v66, v66
	v_exp_f32_e32 v67, v67
	v_exp_f32_e32 v68, v68
	v_exp_f32_e32 v69, v69
	v_exp_f32_e32 v70, v70
	v_exp_f32_e32 v71, v71
	v_exp_f32_e32 v72, v72
	v_exp_f32_e32 v73, v73
	v_exp_f32_e32 v74, v74
	v_exp_f32_e32 v75, v75
	v_exp_f32_e32 v80, v80
	v_exp_f32_e32 v81, v81
	v_exp_f32_e32 v82, v82
	v_exp_f32_e32 v83, v83
	s_nop 0
	v_pk_add_f32 v[84:85], v[64:65], v[66:67]
	v_pk_add_f32 v[86:87], v[68:69], v[70:71]
	v_pk_add_f32 v[76:77], v[72:73], v[74:75]
	v_pk_add_f32 v[78:79], v[80:81], v[82:83]
	v_pk_add_f32 v[84:85], v[84:85], v[86:87]
	v_pk_add_f32 v[76:77], v[76:77], v[78:79]
	s_nop 0
	v_pk_add_f32 v[84:85], v[84:85], v[76:77]
	s_nop 0
	v_add_f32_e32 v84, v84, v85
	v_fma_f32 v145, v145, v0, v84
	v_cvt_pk_bf16_f32 v67, v66, v67
	v_cvt_pk_bf16_f32 v66, v64, v65
	v_cvt_pk_bf16_f32 v68, v68, v69
	v_cvt_pk_bf16_f32 v69, v70, v71
	v_cvt_pk_bf16_f32 v62, v72, v73
	v_cvt_pk_bf16_f32 v63, v74, v75
	v_cvt_pk_bf16_f32 v64, v80, v81
	v_cvt_pk_bf16_f32 v65, v82, v83
	s_branch .LBB0_446
